# hazard-spaced permlane swaps; nt hint on the P4 residual (bf16 x) loads
# speedup vs baseline: 1.0341x; 1.0000x over previous
.LBB0_391:
	s_lshl_b32 s39, s14, 8
	v_add_u32_e32 v176, s39, v180
	v_lshl_or_b32 v128, s46, 8, v182
	v_ashrrev_i32_e32 v177, 31, v176
	v_ashrrev_i32_e32 v129, 31, v128
	v_lshlrev_b64 v[130:131], 11, v[176:177]
	v_lshl_add_u64 v[132:133], s[16:17], 0, v[130:131]
	v_lshlrev_b64 v[130:131], 1, v[128:129]
	v_lshl_add_u64 v[132:133], v[132:133], 0, v[130:131]
	s_mov_b64 s[80:81], 0x8000
	s_mov_b64 s[82:83], 0x28000
	v_lshrrev_b32_e32 v252, 4, v203
	v_lshlrev_b32_e32 v252, 3, v252
	v_mov_b32_e32 v253, 0
	v_lshl_add_u64 v[254:255], v[132:133], 0, v[252:253]
	global_load_dwordx4 v[210:213], v[254:255], off nt
	global_load_dwordx4 v[214:217], v[254:255], off offset:256 nt
	v_lshl_add_u64 v[254:255], v[254:255], 0, s[80:81]
	global_load_dwordx4 v[218:221], v[254:255], off nt
	global_load_dwordx4 v[222:225], v[254:255], off offset:256 nt
	v_lshl_add_u64 v[254:255], v[254:255], 0, s[80:81]
	global_load_dwordx4 v[226:229], v[254:255], off nt
	global_load_dwordx4 v[230:233], v[254:255], off offset:256 nt
	v_lshl_add_u64 v[254:255], v[254:255], 0, s[80:81]
	global_load_dwordx4 v[234:237], v[254:255], off nt
	global_load_dwordx4 v[238:241], v[254:255], off offset:256 nt
	v_lshl_add_u64 v[254:255], v[254:255], 0, s[82:83]
	global_load_dwordx4 v[242:245], v[254:255], off nt
	global_load_dwordx4 v[246:249], v[254:255], off offset:256 nt
	v_lshl_add_u64 v[254:255], v[254:255], 0, s[80:81]
	v_or_b32_e32 v140, 16, v176
	v_ashrrev_i32_e32 v141, 31, v140
	v_lshlrev_b64 v[140:141], 11, v[140:141]
	v_lshl_add_u64 v[140:141], s[16:17], 0, v[140:141]
	v_lshl_add_u64 v[140:141], v[140:141], 0, v[130:131]
	s_waitcnt vmcnt(8)
	v_permlane16_swap_b32_e32 v210, v212
	v_permlane16_swap_b32_e32 v211, v213
	v_permlane16_swap_b32_e32 v214, v216
	v_permlane16_swap_b32_e32 v215, v217
	v_permlane32_swap_b32_e32 v210, v212
	v_permlane32_swap_b32_e32 v211, v213
	v_permlane32_swap_b32_e32 v214, v216
	v_permlane32_swap_b32_e32 v215, v217
	v_mov_b32_e32 v134, v210
	v_mov_b32_e32 v135, v211
	v_mov_b32_e32 v136, v212
	v_mov_b32_e32 v137, v213
	v_mov_b32_e32 v138, v214
	v_mov_b32_e32 v139, v215
	v_mov_b32_e32 v132, v216
	v_mov_b32_e32 v133, v217
	global_load_dwordx4 v[210:213], v[254:255], off nt
	global_load_dwordx4 v[214:217], v[254:255], off offset:256 nt
	v_lshl_add_u64 v[254:255], v[254:255], 0, s[80:81]
	v_lshlrev_b32_e32 v142, 16, v134
	v_and_b32_e32 v143, 0xffff0000, v134
	v_lshlrev_b32_e32 v134, 16, v135
	v_and_b32_e32 v135, 0xffff0000, v135
	v_lshlrev_b32_e32 v144, 16, v136
	v_and_b32_e32 v145, 0xffff0000, v136
	v_lshlrev_b32_e32 v136, 16, v137
	v_and_b32_e32 v137, 0xffff0000, v137
	v_lshlrev_b32_e32 v146, 16, v138
	v_and_b32_e32 v147, 0xffff0000, v138
	v_lshlrev_b32_e32 v138, 16, v139
	v_and_b32_e32 v139, 0xffff0000, v139
	v_lshlrev_b32_e32 v148, 16, v132
	v_and_b32_e32 v149, 0xffff0000, v132
	v_lshlrev_b32_e32 v132, 16, v133
	v_and_b32_e32 v133, 0xffff0000, v133
	v_pk_fma_f32 v[46:47], v[134:135], s[36:37], v[46:47] op_sel_hi:[1,0,1]
	v_pk_fma_f32 v[44:45], v[142:143], s[36:37], v[44:45] op_sel_hi:[1,0,1]
	v_pk_fma_f32 v[42:43], v[136:137], s[36:37], v[42:43] op_sel_hi:[1,0,1]
	v_pk_fma_f32 v[40:41], v[144:145], s[36:37], v[40:41] op_sel_hi:[1,0,1]
	v_pk_fma_f32 v[38:39], v[138:139], s[36:37], v[38:39] op_sel_hi:[1,0,1]
	v_pk_fma_f32 v[36:37], v[146:147], s[36:37], v[36:37] op_sel_hi:[1,0,1]
	v_pk_fma_f32 v[34:35], v[132:133], s[36:37], v[34:35] op_sel_hi:[1,0,1]
	v_pk_fma_f32 v[32:33], v[148:149], s[36:37], v[32:33] op_sel_hi:[1,0,1]
	s_nop 0
	s_waitcnt vmcnt(8)
	v_permlane16_swap_b32_e32 v218, v220
	v_permlane16_swap_b32_e32 v219, v221
	v_permlane16_swap_b32_e32 v222, v224
	v_permlane16_swap_b32_e32 v223, v225
	v_permlane32_swap_b32_e32 v218, v220
	v_permlane32_swap_b32_e32 v219, v221
	v_permlane32_swap_b32_e32 v222, v224
	v_permlane32_swap_b32_e32 v223, v225
	v_mov_b32_e32 v132, v218
	v_mov_b32_e32 v133, v219
	v_mov_b32_e32 v134, v220
	v_mov_b32_e32 v135, v221
	v_mov_b32_e32 v136, v222
	v_mov_b32_e32 v137, v223
	v_mov_b32_e32 v138, v224
	v_mov_b32_e32 v139, v225
	global_load_dwordx4 v[218:221], v[254:255], off nt
	global_load_dwordx4 v[222:225], v[254:255], off offset:256 nt
	v_lshl_add_u64 v[254:255], v[254:255], 0, s[80:81]
	v_or_b32_e32 v140, 32, v176
	v_ashrrev_i32_e32 v141, 31, v140
	v_lshlrev_b64 v[140:141], 11, v[140:141]
	v_lshl_add_u64 v[140:141], s[16:17], 0, v[140:141]
	v_lshl_add_u64 v[140:141], v[140:141], 0, v[130:131]
	v_lshlrev_b32_e32 v142, 16, v132
	v_and_b32_e32 v143, 0xffff0000, v132
	v_lshlrev_b32_e32 v132, 16, v133
	v_and_b32_e32 v133, 0xffff0000, v133
	v_lshlrev_b32_e32 v144, 16, v134
	v_and_b32_e32 v145, 0xffff0000, v134
	v_lshlrev_b32_e32 v134, 16, v135
	v_and_b32_e32 v135, 0xffff0000, v135
	v_lshlrev_b32_e32 v146, 16, v136
	v_and_b32_e32 v147, 0xffff0000, v136
	v_lshlrev_b32_e32 v136, 16, v137
	v_and_b32_e32 v137, 0xffff0000, v137
	v_lshlrev_b32_e32 v148, 16, v138
	v_and_b32_e32 v149, 0xffff0000, v138
	v_lshlrev_b32_e32 v138, 16, v139
	v_and_b32_e32 v139, 0xffff0000, v139
	v_pk_fma_f32 v[90:91], v[132:133], s[36:37], v[90:91] op_sel_hi:[1,0,1]
	v_pk_fma_f32 v[88:89], v[142:143], s[36:37], v[88:89] op_sel_hi:[1,0,1]
	v_pk_fma_f32 v[58:59], v[134:135], s[36:37], v[58:59] op_sel_hi:[1,0,1]
	v_pk_fma_f32 v[56:57], v[144:145], s[36:37], v[56:57] op_sel_hi:[1,0,1]
	v_pk_fma_f32 v[54:55], v[136:137], s[36:37], v[54:55] op_sel_hi:[1,0,1]
	v_pk_fma_f32 v[52:53], v[146:147], s[36:37], v[52:53] op_sel_hi:[1,0,1]
	v_pk_fma_f32 v[50:51], v[138:139], s[36:37], v[50:51] op_sel_hi:[1,0,1]
	v_pk_fma_f32 v[48:49], v[148:149], s[36:37], v[48:49] op_sel_hi:[1,0,1]
	s_nop 0
	s_waitcnt vmcnt(8)
	v_permlane16_swap_b32_e32 v226, v228
	v_permlane16_swap_b32_e32 v227, v229
	v_permlane16_swap_b32_e32 v230, v232
	v_permlane16_swap_b32_e32 v231, v233
	v_permlane32_swap_b32_e32 v226, v228
	v_permlane32_swap_b32_e32 v227, v229
	v_permlane32_swap_b32_e32 v230, v232
	v_permlane32_swap_b32_e32 v231, v233
	v_mov_b32_e32 v132, v226
	v_mov_b32_e32 v133, v227
	v_mov_b32_e32 v134, v228
	v_mov_b32_e32 v135, v229
	v_mov_b32_e32 v136, v230
	v_mov_b32_e32 v137, v231
	v_mov_b32_e32 v138, v232
	v_mov_b32_e32 v139, v233
	global_load_dwordx4 v[226:229], v[254:255], off nt
	global_load_dwordx4 v[230:233], v[254:255], off offset:256 nt
	v_or_b32_e32 v140, 48, v176
	v_ashrrev_i32_e32 v141, 31, v140
	v_lshlrev_b64 v[140:141], 11, v[140:141]
	v_lshl_add_u64 v[140:141], s[16:17], 0, v[140:141]
	v_lshl_add_u64 v[140:141], v[140:141], 0, v[130:131]
	v_lshlrev_b32_e32 v142, 16, v132
	v_and_b32_e32 v143, 0xffff0000, v132
	v_lshlrev_b32_e32 v132, 16, v133
	v_and_b32_e32 v133, 0xffff0000, v133
	v_lshlrev_b32_e32 v144, 16, v134
	v_and_b32_e32 v145, 0xffff0000, v134
	v_lshlrev_b32_e32 v134, 16, v135
	v_and_b32_e32 v135, 0xffff0000, v135
	v_lshlrev_b32_e32 v146, 16, v136
	v_and_b32_e32 v147, 0xffff0000, v136
	v_lshlrev_b32_e32 v136, 16, v137
	v_and_b32_e32 v137, 0xffff0000, v137
	v_lshlrev_b32_e32 v148, 16, v138
	v_and_b32_e32 v149, 0xffff0000, v138
	v_lshlrev_b32_e32 v138, 16, v139
	v_and_b32_e32 v139, 0xffff0000, v139
	v_pk_fma_f32 v[98:99], v[132:133], s[36:37], v[98:99] op_sel_hi:[1,0,1]
	v_pk_fma_f32 v[96:97], v[142:143], s[36:37], v[96:97] op_sel_hi:[1,0,1]
	v_pk_fma_f32 v[82:83], v[134:135], s[36:37], v[82:83] op_sel_hi:[1,0,1]
	v_pk_fma_f32 v[80:81], v[144:145], s[36:37], v[80:81] op_sel_hi:[1,0,1]
	v_pk_fma_f32 v[78:79], v[136:137], s[36:37], v[78:79] op_sel_hi:[1,0,1]
	v_pk_fma_f32 v[76:77], v[146:147], s[36:37], v[76:77] op_sel_hi:[1,0,1]
	v_pk_fma_f32 v[70:71], v[138:139], s[36:37], v[70:71] op_sel_hi:[1,0,1]
	v_pk_fma_f32 v[68:69], v[148:149], s[36:37], v[68:69] op_sel_hi:[1,0,1]
	s_nop 0
	s_waitcnt vmcnt(8)
	v_permlane16_swap_b32_e32 v234, v236
	v_permlane16_swap_b32_e32 v235, v237
	v_permlane16_swap_b32_e32 v238, v240
	v_permlane16_swap_b32_e32 v239, v241
	v_permlane32_swap_b32_e32 v234, v236
	v_permlane32_swap_b32_e32 v235, v237
	v_permlane32_swap_b32_e32 v238, v240
	v_permlane32_swap_b32_e32 v239, v241
	v_mov_b32_e32 v132, v234
	v_mov_b32_e32 v133, v235
	v_mov_b32_e32 v134, v236
	v_mov_b32_e32 v135, v237
	v_mov_b32_e32 v136, v238
	v_mov_b32_e32 v137, v239
	v_mov_b32_e32 v138, v240
	v_mov_b32_e32 v139, v241
	v_add_u32_e32 v140, 0x80, v176
	v_ashrrev_i32_e32 v141, 31, v140
	v_lshlrev_b64 v[140:141], 11, v[140:141]
	v_lshl_add_u64 v[140:141], s[16:17], 0, v[140:141]
	v_lshl_add_u64 v[140:141], v[140:141], 0, v[130:131]
	v_lshlrev_b32_e32 v142, 16, v132
	v_and_b32_e32 v143, 0xffff0000, v132
	v_lshlrev_b32_e32 v132, 16, v133
	v_and_b32_e32 v133, 0xffff0000, v133
	v_lshlrev_b32_e32 v144, 16, v134
	v_and_b32_e32 v145, 0xffff0000, v134
	v_lshlrev_b32_e32 v134, 16, v135
	v_and_b32_e32 v135, 0xffff0000, v135
	v_lshlrev_b32_e32 v146, 16, v136
	v_and_b32_e32 v147, 0xffff0000, v136
	v_lshlrev_b32_e32 v136, 16, v137
	v_and_b32_e32 v137, 0xffff0000, v137
	v_lshlrev_b32_e32 v148, 16, v138
	v_and_b32_e32 v149, 0xffff0000, v138
	v_lshlrev_b32_e32 v138, 16, v139
	v_and_b32_e32 v139, 0xffff0000, v139
	v_pk_fma_f32 v[122:123], v[132:133], s[36:37], v[122:123] op_sel_hi:[1,0,1]
	v_pk_fma_f32 v[120:121], v[142:143], s[36:37], v[120:121] op_sel_hi:[1,0,1]
	v_pk_fma_f32 v[114:115], v[134:135], s[36:37], v[114:115] op_sel_hi:[1,0,1]
	v_pk_fma_f32 v[112:113], v[144:145], s[36:37], v[112:113] op_sel_hi:[1,0,1]
	v_pk_fma_f32 v[106:107], v[136:137], s[36:37], v[106:107] op_sel_hi:[1,0,1]
	v_pk_fma_f32 v[104:105], v[146:147], s[36:37], v[104:105] op_sel_hi:[1,0,1]
	v_pk_fma_f32 v[86:87], v[138:139], s[36:37], v[86:87] op_sel_hi:[1,0,1]
	v_pk_fma_f32 v[84:85], v[148:149], s[36:37], v[84:85] op_sel_hi:[1,0,1]
	s_nop 0
	s_waitcnt vmcnt(6)
	v_permlane16_swap_b32_e32 v242, v244
	v_permlane16_swap_b32_e32 v243, v245
	v_permlane16_swap_b32_e32 v246, v248
	v_permlane16_swap_b32_e32 v247, v249
	v_permlane32_swap_b32_e32 v242, v244
	v_permlane32_swap_b32_e32 v243, v245
	v_permlane32_swap_b32_e32 v246, v248
	v_permlane32_swap_b32_e32 v247, v249
	v_mov_b32_e32 v132, v242
	v_mov_b32_e32 v133, v243
	v_mov_b32_e32 v134, v244
	v_mov_b32_e32 v135, v245
	v_mov_b32_e32 v136, v246
	v_mov_b32_e32 v137, v247
	v_mov_b32_e32 v138, v248
	v_mov_b32_e32 v139, v249
	v_add_u32_e32 v140, 0x90, v176
	v_ashrrev_i32_e32 v141, 31, v140
	v_lshlrev_b64 v[140:141], 11, v[140:141]
	v_lshl_add_u64 v[140:141], s[16:17], 0, v[140:141]
	v_lshl_add_u64 v[140:141], v[140:141], 0, v[130:131]
	v_lshlrev_b32_e32 v142, 16, v132
	v_and_b32_e32 v143, 0xffff0000, v132
	v_lshlrev_b32_e32 v132, 16, v133
	v_and_b32_e32 v133, 0xffff0000, v133
	v_lshlrev_b32_e32 v144, 16, v134
	v_and_b32_e32 v145, 0xffff0000, v134
	v_lshlrev_b32_e32 v134, 16, v135
	v_and_b32_e32 v135, 0xffff0000, v135
	v_lshlrev_b32_e32 v146, 16, v136
	v_and_b32_e32 v147, 0xffff0000, v136
	v_lshlrev_b32_e32 v136, 16, v137
	v_and_b32_e32 v137, 0xffff0000, v137
	v_lshlrev_b32_e32 v148, 16, v138
	v_and_b32_e32 v149, 0xffff0000, v138
	v_lshlrev_b32_e32 v138, 16, v139
	v_and_b32_e32 v139, 0xffff0000, v139
	v_pk_fma_f32 v[14:15], v[132:133], s[36:37], v[14:15] op_sel_hi:[1,0,1]
	v_pk_fma_f32 v[12:13], v[142:143], s[36:37], v[12:13] op_sel_hi:[1,0,1]
	v_pk_fma_f32 v[10:11], v[134:135], s[36:37], v[10:11] op_sel_hi:[1,0,1]
	v_pk_fma_f32 v[8:9], v[144:145], s[36:37], v[8:9] op_sel_hi:[1,0,1]
	v_pk_fma_f32 v[6:7], v[136:137], s[36:37], v[6:7] op_sel_hi:[1,0,1]
	v_pk_fma_f32 v[4:5], v[146:147], s[36:37], v[4:5] op_sel_hi:[1,0,1]
	v_pk_fma_f32 v[2:3], v[138:139], s[36:37], v[2:3] op_sel_hi:[1,0,1]
	v_pk_fma_f32 v[0:1], v[148:149], s[36:37], v[0:1] op_sel_hi:[1,0,1]
	s_nop 0
	s_waitcnt vmcnt(4)
	v_permlane16_swap_b32_e32 v210, v212
	v_permlane16_swap_b32_e32 v211, v213
	v_permlane16_swap_b32_e32 v214, v216
	v_permlane16_swap_b32_e32 v215, v217
	v_permlane32_swap_b32_e32 v210, v212
	v_permlane32_swap_b32_e32 v211, v213
	v_permlane32_swap_b32_e32 v214, v216
	v_permlane32_swap_b32_e32 v215, v217
	v_mov_b32_e32 v132, v210
	v_mov_b32_e32 v133, v211
	v_mov_b32_e32 v134, v212
	v_mov_b32_e32 v135, v213
	v_mov_b32_e32 v136, v214
	v_mov_b32_e32 v137, v215
	v_mov_b32_e32 v138, v216
	v_mov_b32_e32 v139, v217
	v_add_u32_e32 v140, 0xa0, v176
	v_ashrrev_i32_e32 v141, 31, v140
	v_lshlrev_b64 v[140:141], 11, v[140:141]
	v_lshl_add_u64 v[140:141], s[16:17], 0, v[140:141]
	v_lshl_add_u64 v[140:141], v[140:141], 0, v[130:131]
	v_lshlrev_b32_e32 v142, 16, v132
	v_and_b32_e32 v143, 0xffff0000, v132
	v_lshlrev_b32_e32 v132, 16, v133
	v_and_b32_e32 v133, 0xffff0000, v133
	v_lshlrev_b32_e32 v144, 16, v134
	v_and_b32_e32 v145, 0xffff0000, v134
	v_lshlrev_b32_e32 v134, 16, v135
	v_and_b32_e32 v135, 0xffff0000, v135
	v_lshlrev_b32_e32 v146, 16, v136
	v_and_b32_e32 v147, 0xffff0000, v136
	v_lshlrev_b32_e32 v136, 16, v137
	v_and_b32_e32 v137, 0xffff0000, v137
	v_lshlrev_b32_e32 v148, 16, v138
	v_and_b32_e32 v149, 0xffff0000, v138
	v_lshlrev_b32_e32 v138, 16, v139
	v_and_b32_e32 v139, 0xffff0000, v139
	v_pk_fma_f32 v[30:31], v[132:133], s[36:37], v[30:31] op_sel_hi:[1,0,1]
	v_pk_fma_f32 v[28:29], v[142:143], s[36:37], v[28:29] op_sel_hi:[1,0,1]
	v_pk_fma_f32 v[26:27], v[134:135], s[36:37], v[26:27] op_sel_hi:[1,0,1]
	v_pk_fma_f32 v[24:25], v[144:145], s[36:37], v[24:25] op_sel_hi:[1,0,1]
	v_pk_fma_f32 v[22:23], v[136:137], s[36:37], v[22:23] op_sel_hi:[1,0,1]
	v_pk_fma_f32 v[20:21], v[146:147], s[36:37], v[20:21] op_sel_hi:[1,0,1]
	v_pk_fma_f32 v[18:19], v[138:139], s[36:37], v[18:19] op_sel_hi:[1,0,1]
	v_pk_fma_f32 v[16:17], v[148:149], s[36:37], v[16:17] op_sel_hi:[1,0,1]
	v_add_u32_e32 v142, 0xb0, v176
	s_waitcnt vmcnt(2)
	v_permlane16_swap_b32_e32 v218, v220
	v_permlane16_swap_b32_e32 v219, v221
	v_permlane16_swap_b32_e32 v222, v224
	v_permlane16_swap_b32_e32 v223, v225
	v_permlane32_swap_b32_e32 v218, v220
	v_permlane32_swap_b32_e32 v219, v221
	v_permlane32_swap_b32_e32 v222, v224
	v_permlane32_swap_b32_e32 v223, v225
	v_mov_b32_e32 v134, v218
	v_mov_b32_e32 v135, v219
	v_mov_b32_e32 v136, v220
	v_mov_b32_e32 v137, v221
	v_mov_b32_e32 v138, v222
	v_mov_b32_e32 v139, v223
	v_mov_b32_e32 v140, v224
	v_mov_b32_e32 v141, v225
	v_ashrrev_i32_e32 v143, 31, v142
	v_lshlrev_b64 v[142:143], 11, v[142:143]
	v_lshl_add_u64 v[142:143], s[16:17], 0, v[142:143]
	v_lshl_add_u64 v[130:131], v[142:143], 0, v[130:131]
	v_mov_b32_e32 v142, v45
	v_mov_b32_e32 v143, v46
	v_mov_b32_e32 v144, v44
	v_mov_b32_e32 v145, v47
	v_pk_add_f32 v[142:143], v[142:143], v[144:145]
	v_mov_b32_e32 v146, v41
	v_mov_b32_e32 v147, v42
	v_and_b32_e32 v133, 64, v203
	v_xor_b32_e32 v132, 16, v203
	v_add_u32_e32 v133, 64, v133
	v_cmp_lt_i32_e32 vcc, v132, v133
	v_lshlrev_b32_e32 v148, 16, v134
	v_and_b32_e32 v149, 0xffff0000, v134
	v_lshlrev_b32_e32 v134, 16, v135
	v_and_b32_e32 v135, 0xffff0000, v135
	v_lshlrev_b32_e32 v150, 16, v136
	v_and_b32_e32 v151, 0xffff0000, v136
	v_lshlrev_b32_e32 v136, 16, v137
	v_and_b32_e32 v137, 0xffff0000, v137
	v_lshlrev_b32_e32 v152, 16, v138
	v_and_b32_e32 v153, 0xffff0000, v138
	v_lshlrev_b32_e32 v138, 16, v139
	v_and_b32_e32 v139, 0xffff0000, v139
	v_lshlrev_b32_e32 v154, 16, v140
	v_and_b32_e32 v155, 0xffff0000, v140
	v_lshlrev_b32_e32 v140, 16, v141
	v_and_b32_e32 v141, 0xffff0000, v141
	v_pk_fma_f32 v[94:95], v[134:135], s[36:37], v[94:95] op_sel_hi:[1,0,1]
	v_pk_fma_f32 v[92:93], v[148:149], s[36:37], v[92:93] op_sel_hi:[1,0,1]
	v_pk_fma_f32 v[74:75], v[136:137], s[36:37], v[74:75] op_sel_hi:[1,0,1]
	v_pk_fma_f32 v[72:73], v[150:151], s[36:37], v[72:73] op_sel_hi:[1,0,1]
	v_pk_fma_f32 v[66:67], v[138:139], s[36:37], v[66:67] op_sel_hi:[1,0,1]
	v_pk_fma_f32 v[64:65], v[152:153], s[36:37], v[64:65] op_sel_hi:[1,0,1]
	v_pk_fma_f32 v[62:63], v[140:141], s[36:37], v[62:63] op_sel_hi:[1,0,1]
	v_pk_fma_f32 v[60:61], v[154:155], s[36:37], v[60:61] op_sel_hi:[1,0,1]
	v_mov_b32_e32 v134, v40
	v_mov_b32_e32 v135, v43
	v_add_f32_e32 v141, v36, v37
	v_add_f32_e32 v149, v38, v39
	v_mov_b32_e32 v140, v32
	v_mov_b32_e32 v148, v33
	v_pk_add_f32 v[130:131], v[146:147], v[134:135]
	v_pk_add_f32 v[134:135], v[140:141], v[148:149]
	v_add_f32_e32 v140, v142, v143
	v_pk_add_f32 v[130:131], v[130:131], v[130:131] op_sel_hi:[0,1]
	v_mov_b32_e32 v152, v35
	v_add_f32_e32 v153, 0, v140
	v_mov_b32_e32 v130, v34
	v_pk_add_f32 v[130:131], v[130:131], v[152:153]
	v_cndmask_b32_e32 v132, v203, v132, vcc
	v_pk_add_f32 v[130:131], v[134:135], v[130:131]
	v_lshlrev_b32_e32 v132, 2, v132
	v_add_f32_e32 v131, v130, v131
	ds_bpermute_b32 v134, v132, v131
	v_xor_b32_e32 v130, 32, v203
	v_cmp_lt_i32_e32 vcc, v130, v133
	s_waitcnt lgkmcnt(0)
	v_add_f32_e32 v131, v131, v134
	v_cndmask_b32_e32 v130, v203, v130, vcc
	v_lshlrev_b32_e32 v130, 2, v130
	ds_bpermute_b32 v133, v130, v131
	s_waitcnt lgkmcnt(0)
	v_add_f32_e32 v131, v131, v133
	v_fmamk_f32 v134, v131, 0xbc800000, v47
	v_fmamk_f32 v140, v131, 0xbc800000, v45
	v_fmamk_f32 v142, v131, 0xbc800000, v43
	v_fmamk_f32 v146, v131, 0xbc800000, v41
	v_fmamk_f32 v133, v131, 0xbc800000, v46
	v_fmamk_f32 v135, v131, 0xbc800000, v44
	v_fmamk_f32 v141, v131, 0xbc800000, v42
	v_fmamk_f32 v143, v131, 0xbc800000, v40
	v_fmamk_f32 v148, v131, 0xbc800000, v39
	v_fmamk_f32 v152, v131, 0xbc800000, v37
	v_mul_f32_e32 v140, v140, v140
	v_mul_f32_e32 v134, v134, v134
	v_mul_f32_e32 v146, v146, v146
	v_mul_f32_e32 v142, v142, v142
	v_fmamk_f32 v147, v131, 0xbc800000, v38
	v_fmamk_f32 v149, v131, 0xbc800000, v36
	v_fmamk_f32 v154, v131, 0xbc800000, v35
	v_fmamk_f32 v156, v131, 0xbc800000, v33
	v_mul_f32_e32 v152, v152, v152
	v_mul_f32_e32 v148, v148, v148
	v_fmac_f32_e32 v140, v135, v135
	v_fmac_f32_e32 v134, v133, v133
	v_fmac_f32_e32 v146, v143, v143
	v_fmac_f32_e32 v142, v141, v141
	v_fmamk_f32 v153, v131, 0xbc800000, v34
	v_fmamk_f32 v155, v131, 0xbc800000, v32
	v_mul_f32_e32 v156, v156, v156
	v_mul_f32_e32 v154, v154, v154
	v_fmac_f32_e32 v152, v149, v149
	v_fmac_f32_e32 v148, v147, v147
	v_add_f32_e32 v133, v140, v134
	v_add_f32_e32 v134, v146, v142
	v_fmac_f32_e32 v156, v155, v155
	v_fmac_f32_e32 v154, v153, v153
	v_add_f32_e32 v135, v152, v148
	v_add_f32_e32 v133, v133, v134
	v_add_f32_e32 v140, v156, v154
	v_add_f32_e32 v133, v135, v133
	v_add_f32_e32 v133, v140, v133
	ds_bpermute_b32 v134, v132, v133
	s_waitcnt lgkmcnt(0)
	v_add_f32_e32 v133, v133, v134
	ds_bpermute_b32 v134, v130, v133
	s_waitcnt vmcnt(0)
	v_permlane16_swap_b32_e32 v226, v228
	v_permlane16_swap_b32_e32 v227, v229
	v_permlane16_swap_b32_e32 v230, v232
	v_permlane16_swap_b32_e32 v231, v233
	v_permlane32_swap_b32_e32 v226, v228
	v_permlane32_swap_b32_e32 v227, v229
	v_permlane32_swap_b32_e32 v230, v232
	v_permlane32_swap_b32_e32 v231, v233
	v_mov_b32_e32 v136, v226
	v_mov_b32_e32 v137, v227
	v_mov_b32_e32 v138, v228
	v_mov_b32_e32 v139, v229
	v_mov_b32_e32 v150, v230
	v_mov_b32_e32 v151, v231
	v_mov_b32_e32 v144, v232
	v_mov_b32_e32 v145, v233
	v_lshlrev_b32_e32 v140, 16, v136
	v_and_b32_e32 v141, 0xffff0000, v136
	v_lshlrev_b32_e32 v136, 16, v137
	v_and_b32_e32 v137, 0xffff0000, v137
	v_lshlrev_b32_e32 v142, 16, v138
	v_and_b32_e32 v143, 0xffff0000, v138
	v_lshlrev_b32_e32 v138, 16, v139
	v_and_b32_e32 v139, 0xffff0000, v139
	v_lshlrev_b32_e32 v146, 16, v150
	v_and_b32_e32 v147, 0xffff0000, v150
	v_lshlrev_b32_e32 v148, 16, v151
	v_and_b32_e32 v149, 0xffff0000, v151
	v_lshlrev_b32_e32 v150, 16, v144
	v_and_b32_e32 v151, 0xffff0000, v144
	v_lshlrev_b32_e32 v144, 16, v145
	v_and_b32_e32 v145, 0xffff0000, v145
	v_pk_fma_f32 v[126:127], v[136:137], s[36:37], v[126:127] op_sel_hi:[1,0,1]
	v_pk_fma_f32 v[124:125], v[140:141], s[36:37], v[124:125] op_sel_hi:[1,0,1]
	v_pk_fma_f32 v[118:119], v[138:139], s[36:37], v[118:119] op_sel_hi:[1,0,1]
	v_pk_fma_f32 v[116:117], v[142:143], s[36:37], v[116:117] op_sel_hi:[1,0,1]
	v_pk_fma_f32 v[110:111], v[148:149], s[36:37], v[110:111] op_sel_hi:[1,0,1]
	v_pk_fma_f32 v[108:109], v[146:147], s[36:37], v[108:109] op_sel_hi:[1,0,1]
	v_pk_fma_f32 v[102:103], v[144:145], s[36:37], v[102:103] op_sel_hi:[1,0,1]
	v_pk_fma_f32 v[100:101], v[150:151], s[36:37], v[100:101] op_sel_hi:[1,0,1]
	s_nop 0
	s_and_saveexec_b64 s[48:49], s[12:13]
	s_cbranch_execz .LBB0_393
	v_mul_f32_e32 v136, 0x3c800000, v131
	s_waitcnt lgkmcnt(0)
	v_add_f32_e32 v137, v133, v134
	ds_write_b64 v208, v[136:137]
